# down-projection GEMM phases walk their tile list backwards (freshest H panels first), on top of v148
# baseline (speedup 1.0000x reference)
;     __device__ bool next(int i, Unit& u) const {
;         const long L = (long)i * G + c; if (L >= nwg) return false;
;         int wgid = (int)L; { const int q = nwg / NXCD, r = nwg % NXCD, xcd = wgid % NXCD, off = wgid / NXCD; wgid = (xcd < r ? xcd * (q + 1) : r * (q + 1) + (xcd - r) * q) + off; }
;         const int nig = wgm * nN, gid = wgid / nig, fm = gid * wgm, gsz = (nM - fm) < wgm ? (nM - fm) : wgm;
;         u.pm = fm + ((wgid % nig) % gsz); u.pn = (wgid % nig) / gsz; return true;
.LBB0_645:
	v_rcp_iflag_f32_e32 v0, v3
	s_lshr_b32 s1, s34, 3
	v_readlane_b32 s4, v248, 16
	s_or_b32 s1, s1, s4
	v_mul_f32_e32 v0, 0x4f7ffffe, v0
	v_cvt_u32_f32_e32 v0, v0
	v_readlane_b32 s4, v250, 57
	s_sub_i32 s6, 0, s57
	s_mul_i32 s1, s1, s4
	v_readfirstlane_b32 s7, v0
	v_readlane_b32 s4, v250, 58
	s_mul_i32 s6, s6, s7
	s_add_i32 s1, s1, s4
	s_cmp_eq_u32 s39, 1
	s_cbranch_scc1 .Lrev_a
	s_cmp_lg_u32 s39, 6
	s_cbranch_scc1 .Lrev_a_skip
.Lrev_a:
	s_sub_i32 s1, s34, s1
	s_add_i32 s1, s1, -1
.Lrev_a_skip:
	s_mul_hi_u32 s6, s7, s6
	s_abs_i32 s5, s1
	s_add_i32 s7, s7, s6
	s_mul_hi_u32 s6, s5, s7
	s_mul_i32 s7, s6, s57
	s_sub_i32 s5, s5, s7
	s_ashr_i32 s4, s1, 31
	s_add_i32 s7, s6, 1
	s_sub_i32 s8, s5, s57
	s_cmp_ge_u32 s5, s57
	s_cselect_b32 s6, s7, s6
	s_cselect_b32 s5, s8, s5
	s_add_i32 s7, s6, 1
	s_cmp_ge_u32 s5, s57
	s_cselect_b32 s5, s7, s6
	s_xor_b32 s5, s5, s4
	s_sub_i32 s4, s5, s4
	s_mul_i32 s6, s4, s27
	s_sub_i32 s5, s69, s6
	s_min_i32 s7, s5, s27
	s_sext_i32_i16 s5, s7
	v_cvt_f32_i32_e32 v0, s5
	s_mul_i32 s4, s4, s57
	s_sub_i32 s1, s1, s4
	s_sext_i32_i16 s4, s1
	v_cvt_f32_i32_e32 v2, s4
	v_rcp_iflag_f32_e32 v4, v0
	s_xor_b32 s4, s4, s5
	s_ashr_i32 s4, s4, 30
	s_or_b32 s8, s4, 1
	v_mul_f32_e32 v4, v2, v4
	v_trunc_f32_e32 v4, v4
	v_fma_f32 v2, -v4, v0, v2
	v_cvt_i32_f32_e32 v4, v4
	v_cmp_ge_f32_e64 s[4:5], |v2|, |v0|
	s_and_b64 s[4:5], s[4:5], exec
	s_cselect_b32 s4, s8, 0
	v_readfirstlane_b32 s5, v4
	s_add_i32 s4, s5, s4
	s_sext_i32_i16 s53, s4
	s_mul_i32 s4, s4, s7
	s_sub_i32 s1, s1, s4
	s_sext_i32_i16 s1, s1
	s_add_i32 s1, s6, s1
	s_andn2_b64 vcc, exec, s[2:3]
	s_cbranch_vccnz .LBB0_643

;     __device__ bool next(int i, Unit& u) const {
;         const long L = (long)i * G + c; if (L >= nwg) return false;
;         int wgid = (int)L; { const int q = nwg / NXCD, r = nwg % NXCD, xcd = wgid % NXCD, off = wgid / NXCD; wgid = (xcd < r ? xcd * (q + 1) : r * (q + 1) + (xcd - r) * q) + off; }
;         const int nig = wgm * nN, gid = wgid / nig, fm = gid * wgm, gsz = (nM - fm) < wgm ? (nM - fm) : wgm;
;         u.pm = fm + ((wgid % nig) % gsz); u.pn = (wgid % nig) / gsz; return true;
; __device__ __forceinline__ void gemm_phase(LAS unsigned char* lds, const Gemm g, const StaticOrder& S, const Epi& E) {
;     ...
;         const bool has_next = S.next(ui + 1, nxt);
.LBB0_655:
	s_add_i32 s46, s46, 1
	s_mul_i32 s10, s46, s45
	s_mul_hi_u32 s11, s46, s44
	s_add_i32 s11, s11, s10
	s_mul_i32 s10, s46, s44
	s_add_u32 s18, s10, s6
	v_readlane_b32 s10, v250, 12
	s_addc_u32 s19, s11, s10
	v_mov_b64_e32 v[2:3], s[34:35]
	v_cmp_ge_i64_e32 vcc, s[18:19], v[2:3]
	v_cmp_lt_i64_e64 s[40:41], s[18:19], v[2:3]
	s_cbranch_vccnz .LBB0_657
	s_ashr_i32 s10, s18, 31
	s_lshr_b32 s10, s10, 29
	s_add_i32 s10, s18, s10
	s_ashr_i32 s11, s10, 3
	s_and_b32 s10, s10, -8
	s_sub_i32 s10, s18, s10
	s_lshr_b32 s18, s10, 31
	s_or_b32 s18, s3, s18
	s_mul_i32 s10, s18, s10
	s_add_i32 s10, s10, s11
	v_readlane_b32 s98, v248, 33
	s_nop 3
	s_cmp_eq_u32 s98, 1
	s_cbranch_scc1 .Lrev_b
	s_cmp_lg_u32 s98, 6
	s_cbranch_scc1 .Lrev_b_skip
.Lrev_b:
	s_sub_i32 s10, s34, s10
	s_add_i32 s10, s10, -1
.Lrev_b_skip:
	s_abs_i32 s18, s10
	s_mul_hi_u32 s19, s18, s52
	s_mul_i32 s20, s19, s57
	s_sub_i32 s18, s18, s20
	s_ashr_i32 s11, s10, 31
	s_add_i32 s20, s19, 1
	s_sub_i32 s21, s18, s57
	s_cmp_ge_u32 s18, s57
	s_cselect_b32 s19, s20, s19
	s_cselect_b32 s18, s21, s18
	s_add_i32 s20, s19, 1
	s_cmp_ge_u32 s18, s57
	s_cselect_b32 s18, s20, s19
	s_xor_b32 s18, s18, s11
	s_sub_i32 s11, s18, s11
	s_mul_i32 s18, s11, s27
	s_sub_i32 s19, s69, s18
	s_min_i32 s19, s19, s27
	s_abs_i32 s20, s19
	v_cvt_f32_u32_e32 v2, s20
	s_sub_i32 s24, 0, s20
	s_mul_i32 s11, s11, s57
	s_sub_i32 s10, s10, s11
	v_rcp_iflag_f32_e32 v2, v2
	s_abs_i32 s21, s10
	s_xor_b32 s11, s10, s19
	s_ashr_i32 s11, s11, 31
	v_mul_f32_e32 v2, 0x4f7ffffe, v2
	v_cvt_u32_f32_e32 v2, v2
	s_nop 0
	v_readfirstlane_b32 s25, v2
	s_mul_i32 s24, s24, s25
	s_mul_hi_u32 s24, s25, s24
	s_add_i32 s25, s25, s24
	s_mul_hi_u32 s24, s21, s25
	s_mul_i32 s25, s24, s20
	s_sub_i32 s21, s21, s25
	s_add_i32 s25, s24, 1
	s_sub_i32 s38, s21, s20
	s_cmp_ge_u32 s21, s20
	s_cselect_b32 s24, s25, s24
	s_cselect_b32 s21, s38, s21
	s_add_i32 s25, s24, 1
	s_cmp_ge_u32 s21, s20
	s_cselect_b32 s20, s25, s24
	s_xor_b32 s20, s20, s11
	s_sub_i32 s63, s20, s11
	s_mul_i32 s11, s63, s19
	s_sub_i32 s10, s10, s11
	s_add_i32 s94, s10, s18
